# prep LoRA loop: dead xv copy and its load wait removed, second-token LDS operand reads batched
# speedup vs baseline: 1.0025x; 1.0025x over previous
; __device__ void phase_prep(const Ctx& p, int l, LAS unsigned char* lds) {
;     ...
;             const int crow = h * 64 + ct * 16 + fr, c = h * 64 + ct * 16 + 4 * fq;
;             bf16x8 xw[2], xa[2], xg[5], xv;
; #pragma unroll
;             for (int ks = 0; ks < 2; ++ks) { xw[ks] = *(const bf16x8*)(w2T + crow * 64 + ks * 32 + fq * 8); xa[ks] = *(const bf16x8*)(a2T + crow * 64 + ks * 32 + fq * 8); }
; #pragma unroll
;             for (int ks = 0; ks < 5; ++ks) xg[ks] = *(const bf16x8*)(g2T + crow * 160 + ks * 32 + fq * 8);
;             if (l == 1) xv = *(const bf16x8*)(v2T + crow * 32 + fq * 8); else xv = xw[0];
.LBB0_1146:
	v_ashrrev_i32_e32 v123, 31, v122
	v_lshlrev_b64 v[0:1], 1, v[122:123]
	v_lshl_add_u64 v[2:3], v[90:91], 0, v[0:1]
	v_lshl_add_u64 v[0:1], v[92:93], 0, v[0:1]
	v_ashrrev_i32_e32 v125, 31, v124
	global_load_dwordx4 v[40:43], v[2:3], off
	global_load_dwordx4 v[32:35], v[2:3], off offset:64
	global_load_dwordx4 v[36:39], v[0:1], off
	global_load_dwordx4 v[24:27], v[0:1], off offset:64
	v_lshl_add_u64 v[0:1], v[124:125], 1, v[94:95]
	global_load_dwordx4 v[64:67], v[0:1], off
	global_load_dwordx4 v[60:63], v[0:1], off offset:64
	global_load_dwordx4 v[56:59], v[0:1], off offset:128
	global_load_dwordx4 v[52:55], v[0:1], off offset:192
	global_load_dwordx4 v[48:51], v[0:1], off offset:256
	s_and_b64 vcc, exec, s[46:47]
	s_cbranch_vccnz .LBB0_1148
	v_ashrrev_i32_e32 v127, 31, v126
	v_lshl_add_u64 v[0:1], v[126:127], 1, v[96:97]
	global_load_dwordx4 v[28:31], v[0:1], off

; __device__ __forceinline__ float sigm(float x) { return __builtin_amdgcn_rcpf(1.0f + __expf(-x)); }
; __device__ __forceinline__ u32x2 pack4(float a, float b, float c, float d) { u32x2 w; w.x = cvt_pk_bf16(a, b); w.y = cvt_pk_bf16(c, d); return w; }
; __device__ void phase_prep(const Ctx& p, int l, LAS unsigned char* lds) {
;     ...
;                 const LAS bf16_t* yrow = MX + (tt * 16 + fr) * MXS + fq * 8;
;                 f32x4 aW = (f32x4){0.f, 0.f, 0.f, 0.f}, aA = aW, aG = aW, aV = aW;
; #pragma unroll
;                 for (int ks = 0; ks < 2; ++ks) { aW = __builtin_amdgcn_mfma_f32_16x16x32_bf16(xw[ks], *(const LAS bf16x8*)(yrow + 1536 + ks * 32), aW, 0, 0, 0);
;                                                  aA = __builtin_amdgcn_mfma_f32_16x16x32_bf16(xa[ks], *(const LAS bf16x8*)(yrow + 1600 + ks * 32), aA, 0, 0, 0); }
; #pragma unroll
;                 for (int ks = 0; ks < 5; ++ks) aG = __builtin_amdgcn_mfma_f32_16x16x32_bf16(xg[ks], *(const LAS bf16x8*)(yrow + 1664 + ks * 32), aG, 0, 0, 0);
;                 if (l == 1) aV = __builtin_amdgcn_mfma_f32_16x16x32_bf16(xv, *(const LAS bf16x8*)(MID + (tt * 16 + fr) * MIDS + fq * 8), aV, 0, 0, 0);
;     ...
;                     for (int e = 0; e < 4; ++e) { const float vg = sigm(v0a[e] + aV[e]); vv[e] = vv[e] + (vf[e] - vv[e]) * vg; }
;                 }
;                 float ew[4], kh[4], kr4[4], ag4[4];
; #pragma unroll
;                 for (int e = 0; e < 4; ++e) {
;                     ew[e] = 0.60653066f * sigm(w0a[e] + aW[e]);
;                     const float a = sigm(a0a[e] + aA[e]); ag4[e] = a;
;                     const float kr = kk4[e] * kka[e]; kr4[e] = kr; ss[tt] += kr * kr;
;                     kh[e] = kk4[e] * (1.0f + (a - 1.0f) * kaa[e]);
;                     bon[tt] += rr[e] * kh[e] * rka[e];
;                 }
;                 const size_t o = (size_t)t * 512 + c;
;                 *(u32x2*)(oR + o) = rw;
;                 *(u32x2*)(oV + o) = pack4(vv[0], vv[1], vv[2], vv[3]);
;                 *(u32x2*)(oE + o) = pack4(ew[0], ew[1], ew[2], ew[3]);
;                 *(u32x2*)(oK + o) = pack4(kh[0], kh[1], kh[2], kh[3]);
;                 *(u32x2*)(oG + o) = pack4(aG[0], aG[1], aG[2], aG[3]);
;                 *(LAS u32x2*)(mrow) = pack4(ag4[0], ag4[1], ag4[2], ag4[3]);
;                 *(LAS u32x2*)(mrow + 512) = pack4(kr4[0], kr4[1], kr4[2], kr4[3]);
.LBB0_1155:
	s_waitcnt lgkmcnt(0)
	v_lshlrev_b32_e32 v80, 16, v46
	v_and_b32_e32 v81, 0xffff0000, v46
	v_lshlrev_b32_e32 v82, 16, v47
	v_and_b32_e32 v83, 0xffff0000, v47
	s_waitcnt vmcnt(4)
	v_add_f32_e32 v46, v16, v76
	v_add_f32_e32 v47, v17, v77
	v_mul_f32_e32 v46, 0xbfb8aa3b, v46
	v_mul_f32_e32 v47, 0xbfb8aa3b, v47
	v_exp_f32_e32 v46, v46
	v_exp_f32_e32 v47, v47
	s_waitcnt vmcnt(3)
	v_add_f32_e32 v74, v14, v74
	v_mul_f32_e32 v74, 0xbfb8aa3b, v74
	v_add_f32_e32 v46, 1.0, v46
	v_add_f32_e32 v47, 1.0, v47
	v_rcp_f32_e32 v76, v46
	v_add_f32_e32 v46, v12, v72
	v_rcp_f32_e32 v77, v47
	v_add_f32_e32 v47, v13, v73
	v_mul_f32_e32 v46, 0xbfb8aa3b, v46
	v_mul_f32_e32 v47, 0xbfb8aa3b, v47
	v_exp_f32_e32 v46, v46
	v_exp_f32_e32 v47, v47
	v_exp_f32_e32 v74, v74
	s_waitcnt vmcnt(1)
	v_pk_mul_f32 v[158:159], v[76:77], s[28:29] op_sel_hi:[1,0]
	v_add_f32_e32 v46, 1.0, v46
	v_add_f32_e32 v47, 1.0, v47
	v_rcp_f32_e32 v46, v46
	v_rcp_f32_e32 v47, v47
	v_add_f32_e32 v74, 1.0, v74
	v_pk_mul_f32 v[72:73], v[8:9], v[80:81]
	v_add_f32_e32 v78, v18, v78
	v_pk_add_f32 v[76:77], v[46:47], -1.0 op_sel_hi:[1,0]
	v_mul_f32_e32 v78, 0xbfb8aa3b, v78
	v_pk_fma_f32 v[76:77], v[4:5], v[76:77], 1.0 op_sel_hi:[1,1,0]
	v_exp_f32_e32 v78, v78
	v_pk_mul_f32 v[76:77], v[76:77], v[80:81]
	v_rcp_f32_e32 v80, v74
	v_add_f32_e32 v74, v19, v79
	v_mul_f32_e32 v74, 0xbfb8aa3b, v74
	v_exp_f32_e32 v74, v74
	v_add_f32_e32 v78, 1.0, v78
	v_rcp_f32_e32 v78, v78
	v_cvt_pk_bf16_f32 v154, v154, v155
	v_add_f32_e32 v74, 1.0, v74
	v_rcp_f32_e32 v79, v74
	v_add_f32_e32 v74, v15, v75
	v_mul_f32_e32 v74, 0xbfb8aa3b, v74
	v_exp_f32_e32 v74, v74
	v_pk_mul_f32 v[178:179], v[78:79], s[28:29] op_sel_hi:[1,0]
	v_cvt_pk_bf16_f32 v155, v156, v157
	v_cvt_pk_bf16_f32 v68, v68, v69
	v_add_f32_e32 v74, 1.0, v74
	v_rcp_f32_e32 v81, v74
	v_pk_mul_f32 v[74:75], v[10:11], v[82:83]
	v_cvt_pk_bf16_f32 v69, v70, v71
	v_cvt_pk_bf16_f32 v46, v46, v47
	v_pk_add_f32 v[78:79], v[80:81], -1.0 op_sel_hi:[1,0]
	v_cvt_pk_bf16_f32 v47, v80, v81
	v_pk_fma_f32 v[78:79], v[6:7], v[78:79], 1.0 op_sel_hi:[1,1,0]
	s_and_b64 vcc, exec, s[46:47]
	v_pk_mul_f32 v[78:79], v[78:79], v[82:83]
	v_lshl_add_u64 v[82:83], v[116:117], 0, v[148:149]
	v_lshlrev_b64 v[82:83], 1, v[82:83]
	v_lshl_add_u64 v[180:181], s[6:7], 0, v[82:83]
	v_lshl_add_u64 v[156:157], s[42:43], 0, v[82:83]
	global_store_dwordx2 v[180:181], v[44:45], off
	global_store_dwordx2 v[156:157], v[154:155], off
	v_cvt_pk_bf16_f32 v154, v158, v159
	v_cvt_pk_bf16_f32 v155, v178, v179
	v_lshl_add_u64 v[156:157], s[12:13], 0, v[82:83]
	v_lshl_add_u64 v[70:71], s[26:27], 0, v[82:83]
	global_store_dwordx2 v[156:157], v[154:155], off
	v_cvt_pk_bf16_f32 v154, v76, v77
	v_cvt_pk_bf16_f32 v155, v78, v79
	v_lshl_add_u64 v[156:157], s[20:21], 0, v[82:83]
	global_store_dwordx2 v[70:71], v[68:69], off
	v_cvt_pk_bf16_f32 v68, v72, v73
	v_cvt_pk_bf16_f32 v69, v74, v75
	global_store_dwordx2 v[156:157], v[154:155], off
	ds_write2st64_b64 v123, v[46:47], v[68:69] offset1:2
	ds_read_b128 v[68:71], v168 offset:3072
	ds_read_b128 v[80:83], v168 offset:3200
	ds_read_b128 v[154:157], v168 offset:3136
	ds_read_b128 v[178:181], v168 offset:3264
	ds_read_b128 v[192:195], v168 offset:3328
	ds_read_b128 v[196:199], v168 offset:3392
	ds_read_b128 v[200:203], v168 offset:3456
	ds_read_b128 v[204:207], v168 offset:3520
	ds_read_b128 v[208:211], v168 offset:3584
	s_waitcnt lgkmcnt(5)
	v_mfma_f32_16x16x32_bf16 v[40:43], v[40:43], v[68:71], 0
	v_mfma_f32_16x16x32_bf16 v[36:39], v[36:39], v[80:83], 0
	s_waitcnt lgkmcnt(4)
	v_mfma_f32_16x16x32_bf16 v[64:67], v[64:67], v[192:195], 0
	s_waitcnt lgkmcnt(2)
	v_mfma_f32_16x16x32_bf16 v[32:35], v[32:35], v[154:157], v[40:43]
	v_mfma_f32_16x16x32_bf16 v[36:39], v[24:27], v[178:181], v[36:39]
	v_mfma_f32_16x16x32_bf16 v[60:63], v[60:63], v[196:199], v[64:67]
	s_waitcnt lgkmcnt(0)
	s_nop 7
	s_nop 3
	v_mfma_f32_16x16x32_bf16 v[56:59], v[56:59], v[200:203], v[60:63]
	s_nop 7
	s_nop 3
	v_mfma_f32_16x16x32_bf16 v[52:55], v[52:55], v[204:207], v[56:59]
	s_nop 7
	s_nop 3
	v_mfma_f32_16x16x32_bf16 v[46:49], v[48:51], v[208:211], v[52:55]
	s_nop 2
	v_mov_b32_e32 v40, 0
	v_mov_b32_e32 v41, 0
	v_mov_b32_e32 v42, 0
	v_mov_b32_e32 v43, 0
	s_cbranch_vccnz .LBB0_1157
	ds_read_b128 v[24:27], v176 offset:1280
	s_waitcnt lgkmcnt(0)
	v_mfma_f32_16x16x32_bf16 v[40:43], v[28:31], v[24:27], 0
